# k6 plus k_rope (tile 25) epilogue loads issued ahead of the previous row's 16 stores
# baseline (speedup 1.0000x reference)
.LBB0_310:
	v_ashrrev_i32_e32 v151, 31, v150
	s_waitcnt lgkmcnt(0)
	v_lshl_add_u64 v[152:153], v[150:151], 2, s[66:67]
	v_lshlrev_b64 v[154:155], 7, v[150:151]
	global_load_dword v158, v[152:153], off
	v_lshl_add_u64 v[162:163], v[136:137], 0, v[154:155]
	v_lshl_add_u64 v[170:171], v[138:139], 0, v[154:155]
	global_load_dwordx4 v[154:157], v[162:163], off offset:16
	s_nop 0
	global_load_dwordx4 v[162:165], v[162:163], off
	s_nop 0
	global_load_dwordx4 v[166:169], v[170:171], off offset:16
	s_nop 0
	global_load_dwordx4 v[170:173], v[170:171], off
	s_waitcnt vmcnt(0)
	v_pk_mul_f32 v[118:119], v[118:119], v[158:159] op_sel_hi:[1,0]
	v_pk_mul_f32 v[126:127], v[126:127], v[158:159] op_sel_hi:[1,0]
	v_pk_mul_f32 v[116:117], v[116:117], v[158:159] op_sel_hi:[1,0]
	v_pk_mul_f32 v[174:175], v[172:173], v[118:119]
	v_pk_mul_f32 v[118:119], v[164:165], v[118:119]
	v_pk_mul_f32 v[112:113], v[112:113], v[158:159] op_sel_hi:[1,0]
	v_pk_mul_f32 v[124:125], v[124:125], v[158:159] op_sel_hi:[1,0]
	v_pk_mul_f32 v[176:177], v[170:171], v[116:117]
	v_pk_fma_f32 v[174:175], v[164:165], v[126:127], v[174:175] neg_lo:[0,0,1] neg_hi:[0,0,1]
	v_pk_mul_f32 v[116:117], v[162:163], v[116:117]
	v_pk_fma_f32 v[118:119], v[172:173], v[126:127], v[118:119]
	v_pk_mul_f32 v[120:121], v[120:121], v[158:159] op_sel_hi:[1,0]
	v_pk_mul_f32 v[114:115], v[114:115], v[158:159] op_sel_hi:[1,0]
	v_pk_mul_f32 v[126:127], v[112:113], v[166:167]
	v_pk_fma_f32 v[176:177], v[162:163], v[124:125], v[176:177] neg_lo:[0,0,1] neg_hi:[0,0,1]
	v_pk_fma_f32 v[116:117], v[170:171], v[124:125], v[116:117]
	v_pk_mul_f32 v[122:123], v[122:123], v[158:159] op_sel_hi:[1,0]
	v_pk_mul_f32 v[124:125], v[114:115], v[168:169]
	v_pk_fma_f32 v[126:127], v[154:155], v[120:121], v[126:127] neg_lo:[0,0,1] neg_hi:[0,0,1]
	v_pk_mul_f32 v[120:121], v[120:121], v[166:167]
	v_pk_fma_f32 v[124:125], v[156:157], v[122:123], v[124:125] neg_lo:[0,0,1] neg_hi:[0,0,1]
	v_pk_mul_f32 v[122:123], v[122:123], v[168:169]
	v_pk_fma_f32 v[120:121], v[154:155], v[112:113], v[120:121]
	v_pk_fma_f32 v[122:123], v[156:157], v[114:115], v[122:123]
	v_cvt_pk_bf16_f32 v112, v176, v177
	v_cvt_pk_bf16_f32 v113, v174, v175
	v_cvt_pk_bf16_f32 v114, v126, v127
	v_cvt_pk_bf16_f32 v115, v124, v125
	v_cvt_pk_bf16_f32 v116, v116, v117
	v_cvt_pk_bf16_f32 v117, v118, v119
	v_cvt_pk_bf16_f32 v118, v120, v121
	v_mad_i64_i32 v[120:121], s[0:1], v150, s82, v[140:141]
	v_cvt_pk_bf16_f32 v119, v122, v123
	global_load_dword v222, v[152:153], off offset:64
	v_or_b32_e32 v208, 16, v150
	v_ashrrev_i32_e32 v209, 31, v208
	v_lshlrev_b64 v[210:211], 7, v[208:209]
	v_lshl_add_u64 v[214:215], v[136:137], 0, v[210:211]
	v_lshl_add_u64 v[224:225], v[138:139], 0, v[210:211]
	global_load_dwordx4 v[210:213], v[214:215], off offset:16
	global_load_dwordx4 v[214:217], v[214:215], off
	global_load_dwordx4 v[218:221], v[224:225], off offset:16
	global_load_dwordx4 v[224:227], v[224:225], off
	global_store_dwordx4 v[120:121], v[112:115], off offset:256
	global_store_dwordx4 v[120:121], v[116:119], off offset:320
	global_store_dwordx4 v[120:121], v[112:115], off offset:640
	global_store_dwordx4 v[120:121], v[116:119], off offset:704
	global_store_dwordx4 v[120:121], v[112:115], off offset:1024
	global_store_dwordx4 v[120:121], v[116:119], off offset:1088
	global_store_dwordx4 v[120:121], v[112:115], off offset:1408
	global_store_dwordx4 v[120:121], v[116:119], off offset:1472
	global_store_dwordx4 v[120:121], v[112:115], off offset:1792
	global_store_dwordx4 v[120:121], v[116:119], off offset:1856
	global_store_dwordx4 v[120:121], v[112:115], off offset:2176
	global_store_dwordx4 v[120:121], v[116:119], off offset:2240
	global_store_dwordx4 v[120:121], v[112:115], off offset:2560
	global_store_dwordx4 v[120:121], v[116:119], off offset:2624
	global_store_dwordx4 v[120:121], v[112:115], off offset:2944
	global_store_dwordx4 v[120:121], v[116:119], off offset:3008
	v_or_b32_e32 v112, 16, v150
	v_ashrrev_i32_e32 v113, 31, v112
	v_lshlrev_b64 v[114:115], 7, v[112:113]
	v_lshl_add_u64 v[118:119], v[136:137], 0, v[114:115]
	v_lshl_add_u64 v[154:155], v[138:139], 0, v[114:115]
	s_waitcnt vmcnt(16)
	v_mov_b32_e32 v126, v222
	v_mov_b32_e32 v114, v210
	v_mov_b32_e32 v115, v211
	v_mov_b32_e32 v116, v212
	v_mov_b32_e32 v117, v213
	v_mov_b32_e32 v118, v214
	v_mov_b32_e32 v119, v215
	v_mov_b32_e32 v120, v216
	v_mov_b32_e32 v121, v217
	v_mov_b32_e32 v122, v218
	v_mov_b32_e32 v123, v219
	v_mov_b32_e32 v124, v220
	v_mov_b32_e32 v125, v221
	v_mov_b32_e32 v154, v224
	v_mov_b32_e32 v155, v225
	v_mov_b32_e32 v156, v226
	v_mov_b32_e32 v157, v227
	v_pk_mul_f32 v[102:103], v[102:103], v[126:127] op_sel_hi:[1,0]
	v_pk_mul_f32 v[110:111], v[110:111], v[126:127] op_sel_hi:[1,0]
	v_pk_mul_f32 v[100:101], v[100:101], v[126:127] op_sel_hi:[1,0]
	v_pk_mul_f32 v[96:97], v[96:97], v[126:127] op_sel_hi:[1,0]
	v_pk_mul_f32 v[108:109], v[108:109], v[126:127] op_sel_hi:[1,0]
	v_pk_mul_f32 v[104:105], v[104:105], v[126:127] op_sel_hi:[1,0]
	s_nop 0
	v_pk_mul_f32 v[158:159], v[156:157], v[102:103]
	v_pk_mul_f32 v[102:103], v[120:121], v[102:103]
	v_pk_mul_f32 v[162:163], v[154:155], v[100:101]
	v_pk_fma_f32 v[158:159], v[120:121], v[110:111], v[158:159] neg_lo:[0,0,1] neg_hi:[0,0,1]
	v_pk_mul_f32 v[100:101], v[118:119], v[100:101]
	v_pk_fma_f32 v[102:103], v[156:157], v[110:111], v[102:103]
	v_pk_mul_f32 v[98:99], v[98:99], v[126:127] op_sel_hi:[1,0]
	v_pk_mul_f32 v[110:111], v[96:97], v[122:123]
	v_pk_fma_f32 v[162:163], v[118:119], v[108:109], v[162:163] neg_lo:[0,0,1] neg_hi:[0,0,1]
	v_pk_fma_f32 v[100:101], v[154:155], v[108:109], v[100:101]
	v_pk_mul_f32 v[106:107], v[106:107], v[126:127] op_sel_hi:[1,0]
	v_pk_mul_f32 v[108:109], v[98:99], v[124:125]
	v_pk_fma_f32 v[110:111], v[114:115], v[104:105], v[110:111] neg_lo:[0,0,1] neg_hi:[0,0,1]
	v_pk_mul_f32 v[104:105], v[104:105], v[122:123]
	v_pk_fma_f32 v[108:109], v[116:117], v[106:107], v[108:109] neg_lo:[0,0,1] neg_hi:[0,0,1]
	v_pk_mul_f32 v[106:107], v[106:107], v[124:125]
	v_pk_fma_f32 v[104:105], v[114:115], v[96:97], v[104:105]
	v_pk_fma_f32 v[106:107], v[116:117], v[98:99], v[106:107]
	v_cvt_pk_bf16_f32 v96, v162, v163
	v_cvt_pk_bf16_f32 v97, v158, v159
	v_cvt_pk_bf16_f32 v98, v110, v111
	v_cvt_pk_bf16_f32 v99, v108, v109
	v_cvt_pk_bf16_f32 v100, v100, v101
	v_cvt_pk_bf16_f32 v101, v102, v103
	v_cvt_pk_bf16_f32 v102, v104, v105
	v_mad_i64_i32 v[104:105], s[0:1], v112, s82, v[140:141]
	v_cvt_pk_bf16_f32 v103, v106, v107
	global_load_dword v226, v[152:153], off offset:128
	v_or_b32_e32 v208, 32, v150
	v_ashrrev_i32_e32 v209, 31, v208
	v_lshlrev_b64 v[210:211], 7, v[208:209]
	v_lshl_add_u64 v[214:215], v[136:137], 0, v[210:211]
	v_lshl_add_u64 v[222:223], v[138:139], 0, v[210:211]
	global_load_dwordx4 v[210:213], v[214:215], off offset:16
	global_load_dwordx4 v[214:217], v[214:215], off
	global_load_dwordx4 v[218:221], v[222:223], off offset:16
	global_load_dwordx4 v[222:225], v[222:223], off
	global_store_dwordx4 v[104:105], v[96:99], off offset:256
	global_store_dwordx4 v[104:105], v[100:103], off offset:320
	global_store_dwordx4 v[104:105], v[96:99], off offset:640
	global_store_dwordx4 v[104:105], v[100:103], off offset:704
	global_store_dwordx4 v[104:105], v[96:99], off offset:1024
	global_store_dwordx4 v[104:105], v[100:103], off offset:1088
	global_store_dwordx4 v[104:105], v[96:99], off offset:1408
	global_store_dwordx4 v[104:105], v[100:103], off offset:1472
	global_store_dwordx4 v[104:105], v[96:99], off offset:1792
	global_store_dwordx4 v[104:105], v[100:103], off offset:1856
	global_store_dwordx4 v[104:105], v[96:99], off offset:2176
	global_store_dwordx4 v[104:105], v[100:103], off offset:2240
	global_store_dwordx4 v[104:105], v[96:99], off offset:2560
	global_store_dwordx4 v[104:105], v[100:103], off offset:2624
	global_store_dwordx4 v[104:105], v[96:99], off offset:2944
	global_store_dwordx4 v[104:105], v[100:103], off offset:3008
	v_or_b32_e32 v96, 32, v150
	v_ashrrev_i32_e32 v97, 31, v96
	v_lshlrev_b64 v[98:99], 7, v[96:97]
	v_lshl_add_u64 v[102:103], v[136:137], 0, v[98:99]
	v_lshl_add_u64 v[110:111], v[138:139], 0, v[98:99]
	s_waitcnt vmcnt(16)
	v_mov_b32_e32 v114, v226
	v_mov_b32_e32 v98, v210
	v_mov_b32_e32 v99, v211
	v_mov_b32_e32 v100, v212
	v_mov_b32_e32 v101, v213
	v_mov_b32_e32 v102, v214
	v_mov_b32_e32 v103, v215
	v_mov_b32_e32 v104, v216
	v_mov_b32_e32 v105, v217
	v_mov_b32_e32 v106, v218
	v_mov_b32_e32 v107, v219
	v_mov_b32_e32 v108, v220
	v_mov_b32_e32 v109, v221
	v_mov_b32_e32 v110, v222
	v_mov_b32_e32 v111, v223
	v_mov_b32_e32 v112, v224
	v_mov_b32_e32 v113, v225
	v_pk_mul_f32 v[86:87], v[86:87], v[114:115] op_sel_hi:[1,0]
	v_pk_mul_f32 v[94:95], v[94:95], v[114:115] op_sel_hi:[1,0]
	v_pk_mul_f32 v[84:85], v[84:85], v[114:115] op_sel_hi:[1,0]
	v_pk_mul_f32 v[80:81], v[80:81], v[114:115] op_sel_hi:[1,0]
	v_pk_mul_f32 v[92:93], v[92:93], v[114:115] op_sel_hi:[1,0]
	v_pk_mul_f32 v[88:89], v[88:89], v[114:115] op_sel_hi:[1,0]
	s_nop 0
	v_pk_mul_f32 v[116:117], v[112:113], v[86:87]
	v_pk_mul_f32 v[86:87], v[104:105], v[86:87]
	v_pk_mul_f32 v[118:119], v[110:111], v[84:85]
	v_pk_fma_f32 v[116:117], v[104:105], v[94:95], v[116:117] neg_lo:[0,0,1] neg_hi:[0,0,1]
	v_pk_mul_f32 v[84:85], v[102:103], v[84:85]
	v_pk_fma_f32 v[86:87], v[112:113], v[94:95], v[86:87]
	v_pk_mul_f32 v[82:83], v[82:83], v[114:115] op_sel_hi:[1,0]
	v_pk_mul_f32 v[94:95], v[80:81], v[106:107]
	v_pk_fma_f32 v[118:119], v[102:103], v[92:93], v[118:119] neg_lo:[0,0,1] neg_hi:[0,0,1]
	v_pk_fma_f32 v[84:85], v[110:111], v[92:93], v[84:85]
	v_pk_mul_f32 v[90:91], v[90:91], v[114:115] op_sel_hi:[1,0]
	v_pk_mul_f32 v[92:93], v[82:83], v[108:109]
	v_pk_fma_f32 v[94:95], v[98:99], v[88:89], v[94:95] neg_lo:[0,0,1] neg_hi:[0,0,1]
	v_pk_mul_f32 v[88:89], v[88:89], v[106:107]
	v_pk_fma_f32 v[92:93], v[100:101], v[90:91], v[92:93] neg_lo:[0,0,1] neg_hi:[0,0,1]
	v_pk_mul_f32 v[90:91], v[90:91], v[108:109]
	v_pk_fma_f32 v[88:89], v[98:99], v[80:81], v[88:89]
	v_pk_fma_f32 v[90:91], v[100:101], v[82:83], v[90:91]
	v_cvt_pk_bf16_f32 v80, v118, v119
	v_cvt_pk_bf16_f32 v81, v116, v117
	v_cvt_pk_bf16_f32 v82, v94, v95
	v_cvt_pk_bf16_f32 v83, v92, v93
	v_cvt_pk_bf16_f32 v84, v84, v85
	v_cvt_pk_bf16_f32 v85, v86, v87
	v_cvt_pk_bf16_f32 v86, v88, v89
	v_mad_i64_i32 v[88:89], s[0:1], v96, s82, v[140:141]
	v_cvt_pk_bf16_f32 v87, v90, v91
	global_load_dword v226, v[152:153], off offset:192
	v_or_b32_e32 v208, 48, v150
	v_ashrrev_i32_e32 v209, 31, v208
	v_lshlrev_b64 v[210:211], 7, v[208:209]
	v_lshl_add_u64 v[214:215], v[136:137], 0, v[210:211]
	v_lshl_add_u64 v[222:223], v[138:139], 0, v[210:211]
	global_load_dwordx4 v[210:213], v[214:215], off offset:16
	global_load_dwordx4 v[214:217], v[214:215], off
	global_load_dwordx4 v[218:221], v[222:223], off offset:16
	global_load_dwordx4 v[222:225], v[222:223], off
	global_store_dwordx4 v[88:89], v[80:83], off offset:256
	global_store_dwordx4 v[88:89], v[84:87], off offset:320
	global_store_dwordx4 v[88:89], v[80:83], off offset:640
	global_store_dwordx4 v[88:89], v[84:87], off offset:704
	global_store_dwordx4 v[88:89], v[80:83], off offset:1024
	global_store_dwordx4 v[88:89], v[84:87], off offset:1088
	global_store_dwordx4 v[88:89], v[80:83], off offset:1408
	global_store_dwordx4 v[88:89], v[84:87], off offset:1472
	global_store_dwordx4 v[88:89], v[80:83], off offset:1792
	global_store_dwordx4 v[88:89], v[84:87], off offset:1856
	global_store_dwordx4 v[88:89], v[80:83], off offset:2176
	global_store_dwordx4 v[88:89], v[84:87], off offset:2240
	global_store_dwordx4 v[88:89], v[80:83], off offset:2560
	global_store_dwordx4 v[88:89], v[84:87], off offset:2624
	global_store_dwordx4 v[88:89], v[80:83], off offset:2944
	global_store_dwordx4 v[88:89], v[84:87], off offset:3008
	v_or_b32_e32 v80, 48, v150
	v_ashrrev_i32_e32 v81, 31, v80
	v_lshlrev_b64 v[82:83], 7, v[80:81]
	v_lshl_add_u64 v[86:87], v[136:137], 0, v[82:83]
	v_lshl_add_u64 v[94:95], v[138:139], 0, v[82:83]
	s_waitcnt vmcnt(16)
	v_mov_b32_e32 v98, v226
	v_mov_b32_e32 v82, v210
	v_mov_b32_e32 v83, v211
	v_mov_b32_e32 v84, v212
	v_mov_b32_e32 v85, v213
	v_mov_b32_e32 v86, v214
	v_mov_b32_e32 v87, v215
	v_mov_b32_e32 v88, v216
	v_mov_b32_e32 v89, v217
	v_mov_b32_e32 v90, v218
	v_mov_b32_e32 v91, v219
	v_mov_b32_e32 v92, v220
	v_mov_b32_e32 v93, v221
	v_mov_b32_e32 v94, v222
	v_mov_b32_e32 v95, v223
	v_mov_b32_e32 v96, v224
	v_mov_b32_e32 v97, v225
	v_pk_mul_f32 v[70:71], v[70:71], v[98:99] op_sel_hi:[1,0]
	v_pk_mul_f32 v[78:79], v[78:79], v[98:99] op_sel_hi:[1,0]
	v_pk_mul_f32 v[68:69], v[68:69], v[98:99] op_sel_hi:[1,0]
	v_pk_mul_f32 v[64:65], v[64:65], v[98:99] op_sel_hi:[1,0]
	v_pk_mul_f32 v[76:77], v[76:77], v[98:99] op_sel_hi:[1,0]
	v_pk_mul_f32 v[72:73], v[72:73], v[98:99] op_sel_hi:[1,0]
	s_nop 0
	v_pk_mul_f32 v[100:101], v[96:97], v[70:71]
	v_pk_mul_f32 v[70:71], v[88:89], v[70:71]
	v_pk_mul_f32 v[102:103], v[94:95], v[68:69]
	v_pk_fma_f32 v[100:101], v[88:89], v[78:79], v[100:101] neg_lo:[0,0,1] neg_hi:[0,0,1]
	v_pk_mul_f32 v[68:69], v[86:87], v[68:69]
	v_pk_fma_f32 v[70:71], v[96:97], v[78:79], v[70:71]
	v_pk_mul_f32 v[66:67], v[66:67], v[98:99] op_sel_hi:[1,0]
	v_pk_mul_f32 v[78:79], v[64:65], v[90:91]
	v_pk_fma_f32 v[102:103], v[86:87], v[76:77], v[102:103] neg_lo:[0,0,1] neg_hi:[0,0,1]
	v_pk_fma_f32 v[68:69], v[94:95], v[76:77], v[68:69]
	v_pk_mul_f32 v[74:75], v[74:75], v[98:99] op_sel_hi:[1,0]
	v_pk_mul_f32 v[76:77], v[66:67], v[92:93]
	v_pk_fma_f32 v[78:79], v[82:83], v[72:73], v[78:79] neg_lo:[0,0,1] neg_hi:[0,0,1]
	v_pk_mul_f32 v[72:73], v[72:73], v[90:91]
	v_pk_fma_f32 v[76:77], v[84:85], v[74:75], v[76:77] neg_lo:[0,0,1] neg_hi:[0,0,1]
	v_pk_mul_f32 v[74:75], v[74:75], v[92:93]
	v_pk_fma_f32 v[72:73], v[82:83], v[64:65], v[72:73]
	v_pk_fma_f32 v[74:75], v[84:85], v[66:67], v[74:75]
	v_cvt_pk_bf16_f32 v64, v102, v103
	v_cvt_pk_bf16_f32 v65, v100, v101
	v_cvt_pk_bf16_f32 v66, v78, v79
	v_cvt_pk_bf16_f32 v67, v76, v77
	v_cvt_pk_bf16_f32 v68, v68, v69
	v_cvt_pk_bf16_f32 v69, v70, v71
	v_cvt_pk_bf16_f32 v70, v72, v73
	v_mad_i64_i32 v[72:73], s[0:1], v80, s82, v[140:141]
	v_cvt_pk_bf16_f32 v71, v74, v75
	global_load_dword v226, v[152:153], off offset:512
	v_add_u32_e32 v208, 0x80, v150
	v_ashrrev_i32_e32 v209, 31, v208
	v_lshlrev_b64 v[210:211], 7, v[208:209]
	v_lshl_add_u64 v[214:215], v[136:137], 0, v[210:211]
	v_lshl_add_u64 v[222:223], v[138:139], 0, v[210:211]
	global_load_dwordx4 v[210:213], v[214:215], off offset:16
	global_load_dwordx4 v[214:217], v[214:215], off
	global_load_dwordx4 v[218:221], v[222:223], off offset:16
	global_load_dwordx4 v[222:225], v[222:223], off
	global_store_dwordx4 v[72:73], v[64:67], off offset:256
	global_store_dwordx4 v[72:73], v[68:71], off offset:320
	global_store_dwordx4 v[72:73], v[64:67], off offset:640
	global_store_dwordx4 v[72:73], v[68:71], off offset:704
	global_store_dwordx4 v[72:73], v[64:67], off offset:1024
	global_store_dwordx4 v[72:73], v[68:71], off offset:1088
	global_store_dwordx4 v[72:73], v[64:67], off offset:1408
	global_store_dwordx4 v[72:73], v[68:71], off offset:1472
	global_store_dwordx4 v[72:73], v[64:67], off offset:1792
	global_store_dwordx4 v[72:73], v[68:71], off offset:1856
	global_store_dwordx4 v[72:73], v[64:67], off offset:2176
	global_store_dwordx4 v[72:73], v[68:71], off offset:2240
	global_store_dwordx4 v[72:73], v[64:67], off offset:2560
	global_store_dwordx4 v[72:73], v[68:71], off offset:2624
	global_store_dwordx4 v[72:73], v[64:67], off offset:2944
	global_store_dwordx4 v[72:73], v[68:71], off offset:3008
	v_add_u32_e32 v64, 0x80, v150
	v_ashrrev_i32_e32 v65, 31, v64
	v_lshlrev_b64 v[66:67], 7, v[64:65]
	v_lshl_add_u64 v[70:71], v[136:137], 0, v[66:67]
	v_lshl_add_u64 v[78:79], v[138:139], 0, v[66:67]
	s_waitcnt vmcnt(16)
	v_mov_b32_e32 v82, v226
	v_mov_b32_e32 v66, v210
	v_mov_b32_e32 v67, v211
	v_mov_b32_e32 v68, v212
	v_mov_b32_e32 v69, v213
	v_mov_b32_e32 v70, v214
	v_mov_b32_e32 v71, v215
	v_mov_b32_e32 v72, v216
	v_mov_b32_e32 v73, v217
	v_mov_b32_e32 v74, v218
	v_mov_b32_e32 v75, v219
	v_mov_b32_e32 v76, v220
	v_mov_b32_e32 v77, v221
	v_mov_b32_e32 v78, v222
	v_mov_b32_e32 v79, v223
	v_mov_b32_e32 v80, v224
	v_mov_b32_e32 v81, v225
	v_pk_mul_f32 v[54:55], v[54:55], v[82:83] op_sel_hi:[1,0]
	v_pk_mul_f32 v[62:63], v[62:63], v[82:83] op_sel_hi:[1,0]
	v_pk_mul_f32 v[52:53], v[52:53], v[82:83] op_sel_hi:[1,0]
	v_pk_mul_f32 v[48:49], v[48:49], v[82:83] op_sel_hi:[1,0]
	v_pk_mul_f32 v[60:61], v[60:61], v[82:83] op_sel_hi:[1,0]
	v_pk_mul_f32 v[56:57], v[56:57], v[82:83] op_sel_hi:[1,0]
	s_nop 0
	v_pk_mul_f32 v[84:85], v[80:81], v[54:55]
	v_pk_mul_f32 v[54:55], v[72:73], v[54:55]
	v_pk_mul_f32 v[86:87], v[78:79], v[52:53]
	v_pk_fma_f32 v[84:85], v[72:73], v[62:63], v[84:85] neg_lo:[0,0,1] neg_hi:[0,0,1]
	v_pk_mul_f32 v[52:53], v[70:71], v[52:53]
	v_pk_fma_f32 v[54:55], v[80:81], v[62:63], v[54:55]
	v_pk_mul_f32 v[50:51], v[50:51], v[82:83] op_sel_hi:[1,0]
	v_pk_mul_f32 v[62:63], v[48:49], v[74:75]
	v_pk_fma_f32 v[86:87], v[70:71], v[60:61], v[86:87] neg_lo:[0,0,1] neg_hi:[0,0,1]
	v_pk_fma_f32 v[52:53], v[78:79], v[60:61], v[52:53]
	v_pk_mul_f32 v[58:59], v[58:59], v[82:83] op_sel_hi:[1,0]
	v_pk_mul_f32 v[60:61], v[50:51], v[76:77]
	v_pk_fma_f32 v[62:63], v[66:67], v[56:57], v[62:63] neg_lo:[0,0,1] neg_hi:[0,0,1]
	v_pk_mul_f32 v[56:57], v[56:57], v[74:75]
	v_pk_fma_f32 v[60:61], v[68:69], v[58:59], v[60:61] neg_lo:[0,0,1] neg_hi:[0,0,1]
	v_pk_mul_f32 v[58:59], v[58:59], v[76:77]
	v_pk_fma_f32 v[56:57], v[66:67], v[48:49], v[56:57]
	v_pk_fma_f32 v[58:59], v[68:69], v[50:51], v[58:59]
	v_cvt_pk_bf16_f32 v48, v86, v87
	v_cvt_pk_bf16_f32 v49, v84, v85
	v_cvt_pk_bf16_f32 v50, v62, v63
	v_cvt_pk_bf16_f32 v51, v60, v61
	v_cvt_pk_bf16_f32 v52, v52, v53
	v_cvt_pk_bf16_f32 v53, v54, v55
	v_cvt_pk_bf16_f32 v54, v56, v57
	v_mad_i64_i32 v[56:57], s[0:1], v64, s82, v[140:141]
	v_cvt_pk_bf16_f32 v55, v58, v59
	global_load_dword v226, v[152:153], off offset:576
	v_add_u32_e32 v208, 0x90, v150
	v_ashrrev_i32_e32 v209, 31, v208
	v_lshlrev_b64 v[210:211], 7, v[208:209]
	v_lshl_add_u64 v[214:215], v[136:137], 0, v[210:211]
	v_lshl_add_u64 v[222:223], v[138:139], 0, v[210:211]
	global_load_dwordx4 v[210:213], v[214:215], off offset:16
	global_load_dwordx4 v[214:217], v[214:215], off
	global_load_dwordx4 v[218:221], v[222:223], off offset:16
	global_load_dwordx4 v[222:225], v[222:223], off
	global_store_dwordx4 v[56:57], v[48:51], off offset:256
	global_store_dwordx4 v[56:57], v[52:55], off offset:320
	global_store_dwordx4 v[56:57], v[48:51], off offset:640
	global_store_dwordx4 v[56:57], v[52:55], off offset:704
	global_store_dwordx4 v[56:57], v[48:51], off offset:1024
	global_store_dwordx4 v[56:57], v[52:55], off offset:1088
	global_store_dwordx4 v[56:57], v[48:51], off offset:1408
	global_store_dwordx4 v[56:57], v[52:55], off offset:1472
	global_store_dwordx4 v[56:57], v[48:51], off offset:1792
	global_store_dwordx4 v[56:57], v[52:55], off offset:1856
	global_store_dwordx4 v[56:57], v[48:51], off offset:2176
	global_store_dwordx4 v[56:57], v[52:55], off offset:2240
	global_store_dwordx4 v[56:57], v[48:51], off offset:2560
	global_store_dwordx4 v[56:57], v[52:55], off offset:2624
	global_store_dwordx4 v[56:57], v[48:51], off offset:2944
	global_store_dwordx4 v[56:57], v[52:55], off offset:3008
	v_add_u32_e32 v48, 0x90, v150
	v_ashrrev_i32_e32 v49, 31, v48
	v_lshlrev_b64 v[50:51], 7, v[48:49]
	v_lshl_add_u64 v[54:55], v[136:137], 0, v[50:51]
	v_lshl_add_u64 v[62:63], v[138:139], 0, v[50:51]
	s_waitcnt vmcnt(16)
	v_mov_b32_e32 v66, v226
	v_mov_b32_e32 v50, v210
	v_mov_b32_e32 v51, v211
	v_mov_b32_e32 v52, v212
	v_mov_b32_e32 v53, v213
	v_mov_b32_e32 v54, v214
	v_mov_b32_e32 v55, v215
	v_mov_b32_e32 v56, v216
	v_mov_b32_e32 v57, v217
	v_mov_b32_e32 v58, v218
	v_mov_b32_e32 v59, v219
	v_mov_b32_e32 v60, v220
	v_mov_b32_e32 v61, v221
	v_mov_b32_e32 v62, v222
	v_mov_b32_e32 v63, v223
	v_mov_b32_e32 v64, v224
	v_mov_b32_e32 v65, v225
	v_pk_mul_f32 v[38:39], v[38:39], v[66:67] op_sel_hi:[1,0]
	v_pk_mul_f32 v[46:47], v[46:47], v[66:67] op_sel_hi:[1,0]
	v_pk_mul_f32 v[36:37], v[36:37], v[66:67] op_sel_hi:[1,0]
	v_pk_mul_f32 v[32:33], v[32:33], v[66:67] op_sel_hi:[1,0]
	v_pk_mul_f32 v[44:45], v[44:45], v[66:67] op_sel_hi:[1,0]
	v_pk_mul_f32 v[40:41], v[40:41], v[66:67] op_sel_hi:[1,0]
	s_nop 0
	v_pk_mul_f32 v[68:69], v[64:65], v[38:39]
	v_pk_mul_f32 v[38:39], v[56:57], v[38:39]
	v_pk_mul_f32 v[70:71], v[62:63], v[36:37]
	v_pk_fma_f32 v[68:69], v[56:57], v[46:47], v[68:69] neg_lo:[0,0,1] neg_hi:[0,0,1]
	v_pk_mul_f32 v[36:37], v[54:55], v[36:37]
	v_pk_fma_f32 v[38:39], v[64:65], v[46:47], v[38:39]
	v_pk_mul_f32 v[34:35], v[34:35], v[66:67] op_sel_hi:[1,0]
	v_pk_mul_f32 v[46:47], v[32:33], v[58:59]
	v_pk_fma_f32 v[70:71], v[54:55], v[44:45], v[70:71] neg_lo:[0,0,1] neg_hi:[0,0,1]
	v_pk_fma_f32 v[36:37], v[62:63], v[44:45], v[36:37]
	v_pk_mul_f32 v[42:43], v[42:43], v[66:67] op_sel_hi:[1,0]
	v_pk_mul_f32 v[44:45], v[34:35], v[60:61]
	v_pk_fma_f32 v[46:47], v[50:51], v[40:41], v[46:47] neg_lo:[0,0,1] neg_hi:[0,0,1]
	v_pk_mul_f32 v[40:41], v[40:41], v[58:59]
	v_pk_fma_f32 v[44:45], v[52:53], v[42:43], v[44:45] neg_lo:[0,0,1] neg_hi:[0,0,1]
	v_pk_mul_f32 v[42:43], v[42:43], v[60:61]
	v_pk_fma_f32 v[40:41], v[50:51], v[32:33], v[40:41]
	v_pk_fma_f32 v[42:43], v[52:53], v[34:35], v[42:43]
	v_cvt_pk_bf16_f32 v32, v70, v71
	v_cvt_pk_bf16_f32 v33, v68, v69
	v_cvt_pk_bf16_f32 v34, v46, v47
	v_cvt_pk_bf16_f32 v35, v44, v45
	v_cvt_pk_bf16_f32 v36, v36, v37
	v_cvt_pk_bf16_f32 v37, v38, v39
	v_cvt_pk_bf16_f32 v38, v40, v41
	v_mad_i64_i32 v[40:41], s[0:1], v48, s82, v[140:141]
	v_cvt_pk_bf16_f32 v39, v42, v43
	global_load_dword v226, v[152:153], off offset:640
	v_add_u32_e32 v208, 0xa0, v150
	v_ashrrev_i32_e32 v209, 31, v208
	v_lshlrev_b64 v[210:211], 7, v[208:209]
	v_lshl_add_u64 v[214:215], v[136:137], 0, v[210:211]
	v_lshl_add_u64 v[222:223], v[138:139], 0, v[210:211]
	global_load_dwordx4 v[210:213], v[214:215], off offset:16
	global_load_dwordx4 v[214:217], v[214:215], off
	global_load_dwordx4 v[218:221], v[222:223], off offset:16
	global_load_dwordx4 v[222:225], v[222:223], off
	global_store_dwordx4 v[40:41], v[32:35], off offset:256
	global_store_dwordx4 v[40:41], v[36:39], off offset:320
	global_store_dwordx4 v[40:41], v[32:35], off offset:640
	global_store_dwordx4 v[40:41], v[36:39], off offset:704
	global_store_dwordx4 v[40:41], v[32:35], off offset:1024
	global_store_dwordx4 v[40:41], v[36:39], off offset:1088
	global_store_dwordx4 v[40:41], v[32:35], off offset:1408
	global_store_dwordx4 v[40:41], v[36:39], off offset:1472
	global_store_dwordx4 v[40:41], v[32:35], off offset:1792
	global_store_dwordx4 v[40:41], v[36:39], off offset:1856
	global_store_dwordx4 v[40:41], v[32:35], off offset:2176
	global_store_dwordx4 v[40:41], v[36:39], off offset:2240
	global_store_dwordx4 v[40:41], v[32:35], off offset:2560
	global_store_dwordx4 v[40:41], v[36:39], off offset:2624
	global_store_dwordx4 v[40:41], v[32:35], off offset:2944
	global_store_dwordx4 v[40:41], v[36:39], off offset:3008
	v_add_u32_e32 v32, 0xa0, v150
	v_ashrrev_i32_e32 v33, 31, v32
	v_lshlrev_b64 v[34:35], 7, v[32:33]
	v_lshl_add_u64 v[38:39], v[136:137], 0, v[34:35]
	v_lshl_add_u64 v[46:47], v[138:139], 0, v[34:35]
	s_waitcnt vmcnt(16)
	v_mov_b32_e32 v50, v226
	v_mov_b32_e32 v34, v210
	v_mov_b32_e32 v35, v211
	v_mov_b32_e32 v36, v212
	v_mov_b32_e32 v37, v213
	v_mov_b32_e32 v38, v214
	v_mov_b32_e32 v39, v215
	v_mov_b32_e32 v40, v216
	v_mov_b32_e32 v41, v217
	v_mov_b32_e32 v42, v218
	v_mov_b32_e32 v43, v219
	v_mov_b32_e32 v44, v220
	v_mov_b32_e32 v45, v221
	v_mov_b32_e32 v46, v222
	v_mov_b32_e32 v47, v223
	v_mov_b32_e32 v48, v224
	v_mov_b32_e32 v49, v225
	v_pk_mul_f32 v[22:23], v[22:23], v[50:51] op_sel_hi:[1,0]
	v_pk_mul_f32 v[30:31], v[30:31], v[50:51] op_sel_hi:[1,0]
	v_pk_mul_f32 v[20:21], v[20:21], v[50:51] op_sel_hi:[1,0]
	v_pk_mul_f32 v[16:17], v[16:17], v[50:51] op_sel_hi:[1,0]
	v_pk_mul_f32 v[28:29], v[28:29], v[50:51] op_sel_hi:[1,0]
	v_pk_mul_f32 v[24:25], v[24:25], v[50:51] op_sel_hi:[1,0]
	s_nop 0
	v_pk_mul_f32 v[52:53], v[48:49], v[22:23]
	v_pk_mul_f32 v[22:23], v[40:41], v[22:23]
	v_pk_mul_f32 v[54:55], v[46:47], v[20:21]
	v_pk_fma_f32 v[52:53], v[40:41], v[30:31], v[52:53] neg_lo:[0,0,1] neg_hi:[0,0,1]
	v_pk_mul_f32 v[20:21], v[38:39], v[20:21]
	v_pk_fma_f32 v[22:23], v[48:49], v[30:31], v[22:23]
	v_pk_mul_f32 v[18:19], v[18:19], v[50:51] op_sel_hi:[1,0]
	v_pk_mul_f32 v[30:31], v[16:17], v[42:43]
	v_pk_fma_f32 v[54:55], v[38:39], v[28:29], v[54:55] neg_lo:[0,0,1] neg_hi:[0,0,1]
	v_pk_fma_f32 v[20:21], v[46:47], v[28:29], v[20:21]
	v_pk_mul_f32 v[26:27], v[26:27], v[50:51] op_sel_hi:[1,0]
	v_pk_mul_f32 v[28:29], v[18:19], v[44:45]
	v_pk_fma_f32 v[30:31], v[34:35], v[24:25], v[30:31] neg_lo:[0,0,1] neg_hi:[0,0,1]
	v_pk_mul_f32 v[24:25], v[24:25], v[42:43]
	v_pk_fma_f32 v[28:29], v[36:37], v[26:27], v[28:29] neg_lo:[0,0,1] neg_hi:[0,0,1]
	v_pk_mul_f32 v[26:27], v[26:27], v[44:45]
	v_pk_fma_f32 v[24:25], v[34:35], v[16:17], v[24:25]
	v_pk_fma_f32 v[26:27], v[36:37], v[18:19], v[26:27]
	v_cvt_pk_bf16_f32 v16, v54, v55
	v_cvt_pk_bf16_f32 v17, v52, v53
	v_cvt_pk_bf16_f32 v18, v30, v31
	v_cvt_pk_bf16_f32 v19, v28, v29
	v_cvt_pk_bf16_f32 v20, v20, v21
	v_cvt_pk_bf16_f32 v21, v22, v23
	v_cvt_pk_bf16_f32 v22, v24, v25
	v_mad_i64_i32 v[24:25], s[0:1], v32, s82, v[140:141]
	v_cvt_pk_bf16_f32 v23, v26, v27
	global_load_dword v226, v[152:153], off offset:704
	v_add_u32_e32 v208, 0xb0, v150
	v_ashrrev_i32_e32 v209, 31, v208
	v_lshlrev_b64 v[210:211], 7, v[208:209]
	v_lshl_add_u64 v[214:215], v[136:137], 0, v[210:211]
	v_lshl_add_u64 v[222:223], v[138:139], 0, v[210:211]
	global_load_dwordx4 v[210:213], v[214:215], off offset:16
	global_load_dwordx4 v[214:217], v[214:215], off
	global_load_dwordx4 v[218:221], v[222:223], off offset:16
	global_load_dwordx4 v[222:225], v[222:223], off
	global_store_dwordx4 v[24:25], v[16:19], off offset:256
	global_store_dwordx4 v[24:25], v[20:23], off offset:320
	global_store_dwordx4 v[24:25], v[16:19], off offset:640
	global_store_dwordx4 v[24:25], v[20:23], off offset:704
	global_store_dwordx4 v[24:25], v[16:19], off offset:1024
	global_store_dwordx4 v[24:25], v[20:23], off offset:1088
	global_store_dwordx4 v[24:25], v[16:19], off offset:1408
	global_store_dwordx4 v[24:25], v[20:23], off offset:1472
	global_store_dwordx4 v[24:25], v[16:19], off offset:1792
	global_store_dwordx4 v[24:25], v[20:23], off offset:1856
	global_store_dwordx4 v[24:25], v[16:19], off offset:2176
	global_store_dwordx4 v[24:25], v[20:23], off offset:2240
	global_store_dwordx4 v[24:25], v[16:19], off offset:2560
	global_store_dwordx4 v[24:25], v[20:23], off offset:2624
	global_store_dwordx4 v[24:25], v[16:19], off offset:2944
	global_store_dwordx4 v[24:25], v[20:23], off offset:3008
	v_add_u32_e32 v16, 0xb0, v150
	v_ashrrev_i32_e32 v17, 31, v16
	v_lshlrev_b64 v[18:19], 7, v[16:17]
	v_lshl_add_u64 v[22:23], v[136:137], 0, v[18:19]
	v_lshl_add_u64 v[30:31], v[138:139], 0, v[18:19]
	s_waitcnt vmcnt(16)
	v_mov_b32_e32 v34, v226
	v_mov_b32_e32 v18, v210
	v_mov_b32_e32 v19, v211
	v_mov_b32_e32 v20, v212
	v_mov_b32_e32 v21, v213
	v_mov_b32_e32 v22, v214
	v_mov_b32_e32 v23, v215
	v_mov_b32_e32 v24, v216
	v_mov_b32_e32 v25, v217
	v_mov_b32_e32 v26, v218
	v_mov_b32_e32 v27, v219
	v_mov_b32_e32 v28, v220
	v_mov_b32_e32 v29, v221
	v_mov_b32_e32 v30, v222
	v_mov_b32_e32 v31, v223
	v_mov_b32_e32 v32, v224
	v_mov_b32_e32 v33, v225
	v_pk_mul_f32 v[6:7], v[6:7], v[34:35] op_sel_hi:[1,0]
	v_pk_mul_f32 v[14:15], v[14:15], v[34:35] op_sel_hi:[1,0]
	v_pk_mul_f32 v[4:5], v[4:5], v[34:35] op_sel_hi:[1,0]
	v_pk_mul_f32 v[0:1], v[0:1], v[34:35] op_sel_hi:[1,0]
	v_pk_mul_f32 v[12:13], v[12:13], v[34:35] op_sel_hi:[1,0]
	v_pk_mul_f32 v[8:9], v[8:9], v[34:35] op_sel_hi:[1,0]
	s_nop 0
	v_pk_mul_f32 v[36:37], v[32:33], v[6:7]
	v_pk_mul_f32 v[6:7], v[24:25], v[6:7]
	v_pk_mul_f32 v[38:39], v[30:31], v[4:5]
	v_pk_fma_f32 v[36:37], v[24:25], v[14:15], v[36:37] neg_lo:[0,0,1] neg_hi:[0,0,1]
	v_pk_mul_f32 v[4:5], v[22:23], v[4:5]
	v_pk_fma_f32 v[6:7], v[32:33], v[14:15], v[6:7]
	v_pk_mul_f32 v[2:3], v[2:3], v[34:35] op_sel_hi:[1,0]
	v_pk_mul_f32 v[14:15], v[0:1], v[26:27]
	v_pk_fma_f32 v[38:39], v[22:23], v[12:13], v[38:39] neg_lo:[0,0,1] neg_hi:[0,0,1]
	v_pk_fma_f32 v[4:5], v[30:31], v[12:13], v[4:5]
	v_pk_mul_f32 v[10:11], v[10:11], v[34:35] op_sel_hi:[1,0]
	v_pk_mul_f32 v[12:13], v[2:3], v[28:29]
	v_pk_fma_f32 v[14:15], v[18:19], v[8:9], v[14:15] neg_lo:[0,0,1] neg_hi:[0,0,1]
	v_pk_mul_f32 v[8:9], v[8:9], v[26:27]
	v_pk_fma_f32 v[12:13], v[20:21], v[10:11], v[12:13] neg_lo:[0,0,1] neg_hi:[0,0,1]
	v_pk_mul_f32 v[10:11], v[10:11], v[28:29]
	v_pk_fma_f32 v[8:9], v[18:19], v[0:1], v[8:9]
	v_pk_fma_f32 v[10:11], v[20:21], v[2:3], v[10:11]
	v_cvt_pk_bf16_f32 v0, v38, v39
	v_cvt_pk_bf16_f32 v1, v36, v37
	v_cvt_pk_bf16_f32 v2, v14, v15
	v_cvt_pk_bf16_f32 v3, v12, v13
	v_cvt_pk_bf16_f32 v4, v4, v5
	v_cvt_pk_bf16_f32 v5, v6, v7
	v_cvt_pk_bf16_f32 v6, v8, v9
	v_mad_i64_i32 v[8:9], s[0:1], v16, s82, v[140:141]
	v_cvt_pk_bf16_f32 v7, v10, v11
	global_store_dwordx4 v[8:9], v[0:3], off offset:256
	global_store_dwordx4 v[8:9], v[4:7], off offset:320
	global_store_dwordx4 v[8:9], v[0:3], off offset:640
	global_store_dwordx4 v[8:9], v[4:7], off offset:704
	global_store_dwordx4 v[8:9], v[0:3], off offset:1024
	global_store_dwordx4 v[8:9], v[4:7], off offset:1088
	global_store_dwordx4 v[8:9], v[0:3], off offset:1408
	global_store_dwordx4 v[8:9], v[4:7], off offset:1472
	global_store_dwordx4 v[8:9], v[0:3], off offset:1792
	global_store_dwordx4 v[8:9], v[4:7], off offset:1856
	global_store_dwordx4 v[8:9], v[0:3], off offset:2176
	global_store_dwordx4 v[8:9], v[4:7], off offset:2240
	global_store_dwordx4 v[8:9], v[0:3], off offset:2560
	global_store_dwordx4 v[8:9], v[4:7], off offset:2624
	global_store_dwordx4 v[8:9], v[0:3], off offset:2944
	global_store_dwordx4 v[8:9], v[4:7], off offset:3008
